# XB6: XB4 + early L2 write-back by the 2nd-to-last and 9th-to-last workgroup of each XCD
# baseline (speedup 1.0000x reference)
; __device__ __forceinline__ unsigned xb_ld(unsigned* p)              { return __hip_atomic_load(p, __ATOMIC_RELAXED, __HIP_MEMORY_SCOPE_AGENT); }
; __device__ __forceinline__ unsigned xb_add(unsigned* p, unsigned v) { return __hip_atomic_fetch_add(p, v, __ATOMIC_RELAXED, __HIP_MEMORY_SCOPE_AGENT); }
; #define XB_SPIN(cond, bar) do { unsigned _sp = 0; while (cond) { __builtin_amdgcn_s_sleep(1); \
;     if ((++_sp & 255u) == 0u) { if (xb_ld(&(bar)[XB_TMO])) break; if (_sp > XB_SPIN_CAP) { atomicAdd(&(bar)[XB_TMO], 1u); break; } } } } while (0)
; __device__ __forceinline__ void xcd_barrier(const XcdBarrier& b) {
;     ...
;         const unsigned old = xb_add(&bar[XB_XSUB(b.x)], 1u);
;         const unsigned gen = old / nloc;
;         if (old + 1u == (gen + 1u) * nloc) {
;             __builtin_amdgcn_fence(__ATOMIC_RELEASE, "agent");
;             asm volatile("s_waitcnt vmcnt(0)" ::: "memory");
;             const unsigned og = xb_add(&bar[XB_TOP], 1u);
;             const unsigned tg = og / nx;
;             if (og + 1u == (tg + 1u) * nx) xb_add(&bar[XB_TOPGEN], 1u);
;             else XB_SPIN(xb_ld(&bar[XB_TOPGEN]) == tg, bar);
;             __builtin_amdgcn_fence(__ATOMIC_ACQUIRE, "agent");
;             xb_add(&bar[XB_XGEN(b.x)], 1u);
;             asm volatile("s_waitcnt vmcnt(0)" ::: "memory");
;         } else {
;             XB_SPIN(xb_ld(&bar[XB_XGEN(b.x)]) == gen, bar);
;             __builtin_amdgcn_fence(__ATOMIC_ACQUIRE, "agent");
;             asm volatile("s_waitcnt vmcnt(0)" ::: "memory");
.LBB0_412:
	s_or_b64 exec, exec, s[8:9]
	v_cvt_f32_u32_e32 v7, v5
	s_waitcnt vmcnt(0)
	v_readfirstlane_b32 s6, v6
	v_sub_u32_e32 v6, 0, v5
	v_rcp_iflag_f32_e32 v7, v7
	v_add_u32_e32 v8, s6, v2
	v_mul_f32_e32 v7, 0x4f7ffffe, v7
	v_cvt_u32_f32_e32 v7, v7
	v_mul_lo_u32 v2, v6, v7
	v_mul_hi_u32 v2, v7, v2
	v_add_u32_e32 v2, v7, v2
	v_mul_hi_u32 v2, v8, v2
	v_mul_lo_u32 v6, v2, v5
	v_sub_u32_e32 v6, v8, v6
	v_add_u32_e32 v7, 1, v2
	v_cmp_ge_u32_e32 vcc, v6, v5
	s_nop 1
	v_cndmask_b32_e32 v2, v2, v7, vcc
	v_sub_u32_e32 v7, v6, v5
	v_cndmask_b32_e32 v6, v6, v7, vcc
	v_add_u32_e32 v7, 1, v2
	v_cmp_ge_u32_e32 vcc, v6, v5
	v_add_u32_e32 v6, 1, v8
	s_nop 0
	v_cndmask_b32_e32 v2, v2, v7, vcc
	v_mul_lo_u32 v7, v5, v2
	v_add_u32_e32 v5, v7, v5
	v_cmp_ne_u32_e32 vcc, v6, v5
	s_and_saveexec_b64 s[6:7], vcc
	s_xor_b64 s[6:7], exec, s[6:7]
	s_cbranch_execz .LBB0_426
	v_add_u32_e32 v19, 1, v6
	v_cmp_eq_u32_e32 vcc, v19, v5
	s_cbranch_vccnz .Lxb_ewd_1
	v_add_u32_e32 v19, 8, v6
	v_cmp_eq_u32_e32 vcc, v19, v5
	s_cbranch_vccnz .Lxb_ewd_1
	s_branch .Lxb_ew_1
.Lxb_ewd_1:
	buffer_wbl2 sc1

; __device__ __forceinline__ unsigned xb_ld(unsigned* p)              { return __hip_atomic_load(p, __ATOMIC_RELAXED, __HIP_MEMORY_SCOPE_AGENT); }
; __device__ __forceinline__ unsigned xb_add(unsigned* p, unsigned v) { return __hip_atomic_fetch_add(p, v, __ATOMIC_RELAXED, __HIP_MEMORY_SCOPE_AGENT); }
; #define XB_SPIN(cond, bar) do { unsigned _sp = 0; while (cond) { __builtin_amdgcn_s_sleep(1); \
;     if ((++_sp & 255u) == 0u) { if (xb_ld(&(bar)[XB_TMO])) break; if (_sp > XB_SPIN_CAP) { atomicAdd(&(bar)[XB_TMO], 1u); break; } } } } while (0)
; __device__ __forceinline__ void xcd_barrier(const XcdBarrier& b) {
;     ...
;         const unsigned old = xb_add(&bar[XB_XSUB(b.x)], 1u);
;         const unsigned gen = old / nloc;
;         if (old + 1u == (gen + 1u) * nloc) {
;             __builtin_amdgcn_fence(__ATOMIC_RELEASE, "agent");
;             asm volatile("s_waitcnt vmcnt(0)" ::: "memory");
;             const unsigned og = xb_add(&bar[XB_TOP], 1u);
;             const unsigned tg = og / nx;
;             if (og + 1u == (tg + 1u) * nx) xb_add(&bar[XB_TOPGEN], 1u);
;             else XB_SPIN(xb_ld(&bar[XB_TOPGEN]) == tg, bar);
;             __builtin_amdgcn_fence(__ATOMIC_ACQUIRE, "agent");
;             xb_add(&bar[XB_XGEN(b.x)], 1u);
;             asm volatile("s_waitcnt vmcnt(0)" ::: "memory");
;         } else {
;             XB_SPIN(xb_ld(&bar[XB_XGEN(b.x)]) == gen, bar);
;             __builtin_amdgcn_fence(__ATOMIC_ACQUIRE, "agent");
;             asm volatile("s_waitcnt vmcnt(0)" ::: "memory");
.LBB0_654:
	s_or_b64 exec, exec, s[6:7]
	v_cvt_f32_u32_e32 v7, v5
	s_waitcnt vmcnt(0)
	v_readfirstlane_b32 s4, v6
	v_sub_u32_e32 v6, 0, v5
	v_rcp_iflag_f32_e32 v7, v7
	v_add_u32_e32 v8, s4, v2
	v_mul_f32_e32 v7, 0x4f7ffffe, v7
	v_cvt_u32_f32_e32 v7, v7
	v_mul_lo_u32 v2, v6, v7
	v_mul_hi_u32 v2, v7, v2
	v_add_u32_e32 v2, v7, v2
	v_mul_hi_u32 v2, v8, v2
	v_mul_lo_u32 v6, v2, v5
	v_sub_u32_e32 v6, v8, v6
	v_add_u32_e32 v7, 1, v2
	v_cmp_ge_u32_e32 vcc, v6, v5
	s_nop 1
	v_cndmask_b32_e32 v2, v2, v7, vcc
	v_sub_u32_e32 v7, v6, v5
	v_cndmask_b32_e32 v6, v6, v7, vcc
	v_add_u32_e32 v7, 1, v2
	v_cmp_ge_u32_e32 vcc, v6, v5
	v_add_u32_e32 v6, 1, v8
	s_nop 0
	v_cndmask_b32_e32 v2, v2, v7, vcc
	v_mul_lo_u32 v7, v5, v2
	v_add_u32_e32 v5, v7, v5
	v_cmp_ne_u32_e32 vcc, v6, v5
	s_and_saveexec_b64 s[4:5], vcc
	s_xor_b64 s[4:5], exec, s[4:5]
	s_cbranch_execz .LBB0_668
	v_add_u32_e32 v19, 1, v6
	v_cmp_eq_u32_e32 vcc, v19, v5
	s_cbranch_vccnz .Lxb_ewd_2
	v_add_u32_e32 v19, 8, v6
	v_cmp_eq_u32_e32 vcc, v19, v5
	s_cbranch_vccnz .Lxb_ewd_2
	s_branch .Lxb_ew_2

; __device__ __forceinline__ unsigned xb_ld(unsigned* p)              { return __hip_atomic_load(p, __ATOMIC_RELAXED, __HIP_MEMORY_SCOPE_AGENT); }
; __device__ __forceinline__ unsigned xb_add(unsigned* p, unsigned v) { return __hip_atomic_fetch_add(p, v, __ATOMIC_RELAXED, __HIP_MEMORY_SCOPE_AGENT); }
; #define XB_SPIN(cond, bar) do { unsigned _sp = 0; while (cond) { __builtin_amdgcn_s_sleep(1); \
;     if ((++_sp & 255u) == 0u) { if (xb_ld(&(bar)[XB_TMO])) break; if (_sp > XB_SPIN_CAP) { atomicAdd(&(bar)[XB_TMO], 1u); break; } } } } while (0)
; __device__ __forceinline__ void xcd_barrier(const XcdBarrier& b) {
;     ...
;         const unsigned old = xb_add(&bar[XB_XSUB(b.x)], 1u);
;         const unsigned gen = old / nloc;
;         if (old + 1u == (gen + 1u) * nloc) {
;             __builtin_amdgcn_fence(__ATOMIC_RELEASE, "agent");
;             asm volatile("s_waitcnt vmcnt(0)" ::: "memory");
;             const unsigned og = xb_add(&bar[XB_TOP], 1u);
;             const unsigned tg = og / nx;
;             if (og + 1u == (tg + 1u) * nx) xb_add(&bar[XB_TOPGEN], 1u);
;             else XB_SPIN(xb_ld(&bar[XB_TOPGEN]) == tg, bar);
;             __builtin_amdgcn_fence(__ATOMIC_ACQUIRE, "agent");
;             xb_add(&bar[XB_XGEN(b.x)], 1u);
;             asm volatile("s_waitcnt vmcnt(0)" ::: "memory");
;         } else {
;             XB_SPIN(xb_ld(&bar[XB_XGEN(b.x)]) == gen, bar);
;             __builtin_amdgcn_fence(__ATOMIC_ACQUIRE, "agent");
;             asm volatile("s_waitcnt vmcnt(0)" ::: "memory");
.LBB0_1167:
	s_or_b64 exec, exec, s[14:15]
	v_cvt_f32_u32_e32 v7, v5
	s_waitcnt vmcnt(0)
	v_readfirstlane_b32 s6, v6
	v_sub_u32_e32 v6, 0, v5
	v_rcp_iflag_f32_e32 v7, v7
	v_add_u32_e32 v8, s6, v2
	v_mul_f32_e32 v7, 0x4f7ffffe, v7
	v_cvt_u32_f32_e32 v7, v7
	v_mul_lo_u32 v2, v6, v7
	v_mul_hi_u32 v2, v7, v2
	v_add_u32_e32 v2, v7, v2
	v_mul_hi_u32 v2, v8, v2
	v_mul_lo_u32 v6, v2, v5
	v_sub_u32_e32 v6, v8, v6
	v_add_u32_e32 v7, 1, v2
	v_cmp_ge_u32_e32 vcc, v6, v5
	s_nop 1
	v_cndmask_b32_e32 v2, v2, v7, vcc
	v_sub_u32_e32 v7, v6, v5
	v_cndmask_b32_e32 v6, v6, v7, vcc
	v_add_u32_e32 v7, 1, v2
	v_cmp_ge_u32_e32 vcc, v6, v5
	v_add_u32_e32 v6, 1, v8
	s_nop 0
	v_cndmask_b32_e32 v2, v2, v7, vcc
	v_mul_lo_u32 v7, v5, v2
	v_add_u32_e32 v5, v7, v5
	v_cmp_ne_u32_e32 vcc, v6, v5
	s_and_saveexec_b64 s[6:7], vcc
	s_xor_b64 s[6:7], exec, s[6:7]
	s_cbranch_execz .LBB0_1181
	v_add_u32_e32 v19, 1, v6
	v_cmp_eq_u32_e32 vcc, v19, v5
	s_cbranch_vccnz .Lxb_ewd_7
	v_add_u32_e32 v19, 8, v6
	v_cmp_eq_u32_e32 vcc, v19, v5
	s_cbranch_vccnz .Lxb_ewd_7
	s_branch .Lxb_ew_7
